# attn0 window tiles: bias column offsets and window positions tabulated once per sample item instead of recomputed per tile
# speedup vs baseline: 1.0043x; 1.0043x over previous
.LBB0_610:
	s_andn2_saveexec_b64 s[10:11], s[0:1]
	s_cbranch_execz .LBB0_589
	v_lshlrev_b32_e32 v2, 1, v156
	v_lshl_or_b32 v2, v154, 5, v2
	v_add_u32_e32 v177, 0, v174
	v_sub_u32_e32 v142, v177, v167
	v_sub_u32_e32 v185, v177, v165
	v_add_u32_e32 v185, 15, v185
	v_med3_i32 v238, v185, 0, 30
	v_lshlrev_b32_e32 v238, 2, v238
	v_add_u32_e32 v185, 32, v185
	v_med3_i32 v204, v185, 0, 30
	v_lshlrev_b32_e32 v204, 2, v204
	v_add_u32_e32 v177, 1, v174
	v_sub_u32_e32 v143, v177, v167
	v_sub_u32_e32 v185, v177, v165
	v_add_u32_e32 v185, 15, v185
	v_med3_i32 v239, v185, 0, 30
	v_lshlrev_b32_e32 v239, 2, v239
	v_add_u32_e32 v185, 32, v185
	v_med3_i32 v205, v185, 0, 30
	v_lshlrev_b32_e32 v205, 2, v205
	v_add_u32_e32 v177, 2, v174
	v_sub_u32_e32 v144, v177, v167
	v_sub_u32_e32 v185, v177, v165
	v_add_u32_e32 v185, 15, v185
	v_med3_i32 v240, v185, 0, 30
	v_lshlrev_b32_e32 v240, 2, v240
	v_add_u32_e32 v185, 32, v185
	v_med3_i32 v206, v185, 0, 30
	v_lshlrev_b32_e32 v206, 2, v206
	v_add_u32_e32 v177, 3, v174
	v_sub_u32_e32 v145, v177, v167
	v_sub_u32_e32 v185, v177, v165
	v_add_u32_e32 v185, 15, v185
	v_med3_i32 v241, v185, 0, 30
	v_lshlrev_b32_e32 v241, 2, v241
	v_add_u32_e32 v185, 32, v185
	v_med3_i32 v207, v185, 0, 30
	v_lshlrev_b32_e32 v207, 2, v207
	v_add_u32_e32 v177, 8, v174
	v_sub_u32_e32 v146, v177, v167
	v_sub_u32_e32 v185, v177, v165
	v_add_u32_e32 v185, 15, v185
	v_med3_i32 v242, v185, 0, 30
	v_lshlrev_b32_e32 v242, 2, v242
	v_add_u32_e32 v185, 32, v185
	v_med3_i32 v208, v185, 0, 30
	v_lshlrev_b32_e32 v208, 2, v208
	v_add_u32_e32 v177, 9, v174
	v_sub_u32_e32 v147, v177, v167
	v_sub_u32_e32 v185, v177, v165
	v_add_u32_e32 v185, 15, v185
	v_med3_i32 v243, v185, 0, 30
	v_lshlrev_b32_e32 v243, 2, v243
	v_add_u32_e32 v185, 32, v185
	v_med3_i32 v209, v185, 0, 30
	v_lshlrev_b32_e32 v209, 2, v209
	v_add_u32_e32 v177, 10, v174
	v_sub_u32_e32 v148, v177, v167
	v_sub_u32_e32 v185, v177, v165
	v_add_u32_e32 v185, 15, v185
	v_med3_i32 v244, v185, 0, 30
	v_lshlrev_b32_e32 v244, 2, v244
	v_add_u32_e32 v185, 32, v185
	v_med3_i32 v210, v185, 0, 30
	v_lshlrev_b32_e32 v210, 2, v210
	v_add_u32_e32 v177, 11, v174
	v_sub_u32_e32 v149, v177, v167
	v_sub_u32_e32 v185, v177, v165
	v_add_u32_e32 v185, 15, v185
	v_med3_i32 v245, v185, 0, 30
	v_lshlrev_b32_e32 v245, 2, v245
	v_add_u32_e32 v185, 32, v185
	v_med3_i32 v211, v185, 0, 30
	v_lshlrev_b32_e32 v211, 2, v211
	v_add_u32_e32 v177, 16, v174
	v_sub_u32_e32 v158, v177, v167
	v_sub_u32_e32 v185, v177, v165
	v_add_u32_e32 v185, 15, v185
	v_med3_i32 v246, v185, 0, 30
	v_lshlrev_b32_e32 v246, 2, v246
	v_add_u32_e32 v185, 32, v185
	v_med3_i32 v212, v185, 0, 30
	v_lshlrev_b32_e32 v212, 2, v212
	v_add_u32_e32 v177, 17, v174
	v_sub_u32_e32 v160, v177, v167
	v_sub_u32_e32 v185, v177, v165
	v_add_u32_e32 v185, 15, v185
	v_med3_i32 v247, v185, 0, 30
	v_lshlrev_b32_e32 v247, 2, v247
	v_add_u32_e32 v185, 32, v185
	v_med3_i32 v213, v185, 0, 30
	v_lshlrev_b32_e32 v213, 2, v213
	v_add_u32_e32 v177, 18, v174
	v_sub_u32_e32 v162, v177, v167
	v_sub_u32_e32 v185, v177, v165
	v_add_u32_e32 v185, 15, v185
	v_med3_i32 v248, v185, 0, 30
	v_lshlrev_b32_e32 v248, 2, v248
	v_add_u32_e32 v185, 32, v185
	v_med3_i32 v214, v185, 0, 30
	v_lshlrev_b32_e32 v214, 2, v214
	v_add_u32_e32 v177, 19, v174
	v_sub_u32_e32 v164, v177, v167
	v_sub_u32_e32 v185, v177, v165
	v_add_u32_e32 v185, 15, v185
	v_med3_i32 v249, v185, 0, 30
	v_lshlrev_b32_e32 v249, 2, v249
	v_add_u32_e32 v185, 32, v185
	v_med3_i32 v136, v185, 0, 30
	v_lshlrev_b32_e32 v136, 2, v136
	v_add_u32_e32 v177, 24, v174
	v_sub_u32_e32 v166, v177, v167
	v_sub_u32_e32 v185, v177, v165
	v_add_u32_e32 v185, 15, v185
	v_med3_i32 v250, v185, 0, 30
	v_lshlrev_b32_e32 v250, 2, v250
	v_add_u32_e32 v185, 32, v185
	v_med3_i32 v137, v185, 0, 30
	v_lshlrev_b32_e32 v137, 2, v137
	v_add_u32_e32 v177, 25, v174
	v_sub_u32_e32 v168, v177, v167
	v_sub_u32_e32 v185, v177, v165
	v_add_u32_e32 v185, 15, v185
	v_med3_i32 v251, v185, 0, 30
	v_lshlrev_b32_e32 v251, 2, v251
	v_add_u32_e32 v185, 32, v185
	v_med3_i32 v138, v185, 0, 30
	v_lshlrev_b32_e32 v138, 2, v138
	v_add_u32_e32 v177, 26, v174
	v_sub_u32_e32 v169, v177, v167
	v_sub_u32_e32 v185, v177, v165
	v_add_u32_e32 v185, 15, v185
	v_med3_i32 v252, v185, 0, 30
	v_lshlrev_b32_e32 v252, 2, v252
	v_add_u32_e32 v185, 32, v185
	v_med3_i32 v139, v185, 0, 30
	v_lshlrev_b32_e32 v139, 2, v139
	v_add_u32_e32 v177, 27, v174
	v_sub_u32_e32 v171, v177, v167
	v_sub_u32_e32 v185, v177, v165
	v_add_u32_e32 v185, 15, v185
	v_med3_i32 v253, v185, 0, 30
	v_lshlrev_b32_e32 v253, 2, v253
	v_add_u32_e32 v185, 32, v185
	v_med3_i32 v140, v185, 0, 30
	v_lshlrev_b32_e32 v140, 2, v140
	s_waitcnt vmcnt(0) lgkmcnt(0)
	s_barrier
	s_load_dwordx2 s[0:1], s[30:31], 0xb8
	v_bfe_u32 v183, v1, 4, 4
	s_nop 5
	v_mul_u32_u24_e32 v4, 0x1d1, v183
	v_add_lshl_u32 v4, v150, v4, 2
	v_mov_b32_e32 v5, v3
	s_waitcnt lgkmcnt(0)
	v_lshl_add_u64 v[4:5], s[0:1], 0, v[4:5]
	s_mov_b64 s[0:1], 0
	v_mov_b32_e32 v6, v216
	v_mov_b32_e32 v7, v215
	s_movk_i32 s3, 0xd0

.LBB0_622:
	v_mov_b32_e32 v39, v3
	v_mul_u32_u24_e32 v133, s0, v154
	v_lshl_add_u64 v[114:115], v[38:39], 1, v[40:41]
	v_or_b32_e32 v38, v133, v156
	v_lshlrev_b32_e32 v38, 1, v38
	v_lshl_add_u64 v[116:117], v[114:115], 0, v[38:39]
	v_xor_b32_e32 v38, 0x80000000, v132
	v_mov_b32_e32 v39, v38
	v_mov_b32_e32 v40, v38
	v_mov_b32_e32 v41, v38
	v_mov_b32_e32 v42, v38
	v_mov_b32_e32 v43, v38
	v_mov_b32_e32 v44, v38
	v_mov_b32_e32 v45, v38
	v_mov_b32_e32 v46, v38
	v_mov_b32_e32 v47, v38
	v_mov_b32_e32 v48, v38
	v_mov_b32_e32 v49, v38
	v_mov_b32_e32 v50, v38
	v_mov_b32_e32 v51, v38
	v_mov_b32_e32 v52, v38
	v_mov_b32_e32 v53, v38
	s_lshl_b32 s1, s0, 5
	v_mov_b32_e32 v135, v3
	s_waitcnt vmcnt(11)
	v_mfma_f32_32x32x16_bf16 v[38:53], v[106:109], v[54:57], v[38:53]
	v_mov_b32_e32 v106, s1
	v_mad_u32_u24 v134, s0, v154, v106
	v_or_b32_e32 v106, v134, v156
	v_lshlrev_b32_e32 v106, 1, v106
	v_mov_b32_e32 v107, v3
	v_lshl_add_u64 v[106:107], v[114:115], 0, v[106:107]
	v_add_lshl_u32 v134, v134, v156, 1
	s_waitcnt vmcnt(10)
	v_mfma_f32_32x32x16_bf16 v[38:53], v[102:105], v[58:61], v[38:53]
	global_load_dwordx4 v[102:105], v[116:117], off
	s_nop 0
	global_load_dwordx4 v[106:109], v[106:107], off
	v_add_lshl_u32 v116, v133, v156, 1
	v_mov_b32_e32 v117, v3
	v_lshl_add_u64 v[116:117], v[114:115], 0, v[116:117]
	v_lshl_add_u64 v[114:115], v[114:115], 0, v[134:135]
	s_cmp_gt_u32 s15, 7
	s_cselect_b64 s[4:5], -1, 0
	s_waitcnt vmcnt(11)
	v_mfma_f32_32x32x16_bf16 v[38:53], v[110:113], v[62:65], v[38:53]
	global_load_dwordx4 v[110:113], v[116:117], off offset:32
	s_nop 0
	global_load_dwordx4 v[114:117], v[114:115], off offset:32
	s_and_b32 s14, s3, 32
	s_lshr_b32 s13, s12, 1
	s_cmp_lt_u32 s15, 8
	s_waitcnt vmcnt(12)
	v_mfma_f32_32x32x16_bf16 v[38:53], v[118:121], v[66:69], v[38:53]
	v_or_b32_e32 v118, s14, v174
	s_cbranch_scc1 .La0_nobias
	v_add_u32_e32 v236, s13, v131
	s_movk_i32 s15, 0x7c
	v_mul_lo_u32 v236, v236, s15
	v_add_u32_e32 v236, v151, v236
	v_mov_b32_e32 v237, 0xf149f2ca
	s_cmp_eq_u32 s14, 0
	s_cbranch_scc0 .La0_p1
	v_add_u32_e32 v235, v238, v236
	ds_read_b32 v188, v235 offset:868
	v_add_u32_e32 v235, v239, v236
	ds_read_b32 v189, v235 offset:868
	v_add_u32_e32 v235, v240, v236
	ds_read_b32 v190, v235 offset:868
	v_add_u32_e32 v235, v241, v236
	ds_read_b32 v191, v235 offset:868
	v_add_u32_e32 v235, v242, v236
	ds_read_b32 v192, v235 offset:868
	v_add_u32_e32 v235, v243, v236
	ds_read_b32 v193, v235 offset:868
	v_add_u32_e32 v235, v244, v236
	ds_read_b32 v194, v235 offset:868
	v_add_u32_e32 v235, v245, v236
	ds_read_b32 v195, v235 offset:868
	v_add_u32_e32 v235, v246, v236
	ds_read_b32 v196, v235 offset:868
	v_add_u32_e32 v235, v247, v236
	ds_read_b32 v197, v235 offset:868
	v_add_u32_e32 v235, v248, v236
	ds_read_b32 v198, v235 offset:868
	v_add_u32_e32 v235, v249, v236
	ds_read_b32 v199, v235 offset:868
	v_add_u32_e32 v235, v250, v236
	ds_read_b32 v200, v235 offset:868
	v_add_u32_e32 v235, v251, v236
	ds_read_b32 v201, v235 offset:868
	v_add_u32_e32 v235, v252, v236
	ds_read_b32 v202, v235 offset:868
	v_add_u32_e32 v235, v253, v236
	ds_read_b32 v203, v235 offset:868
	v_cmp_gt_u32_e32 vcc, 16, v142
	s_waitcnt lgkmcnt(15)
	v_add_f32_e32 v38, v38, v188
	v_cndmask_b32_e32 v38, v237, v38, vcc
	v_cmp_gt_u32_e32 vcc, 16, v143
	s_waitcnt lgkmcnt(14)
	v_add_f32_e32 v39, v39, v189
	v_cndmask_b32_e32 v39, v237, v39, vcc
	v_cmp_gt_u32_e32 vcc, 16, v144
	s_waitcnt lgkmcnt(13)
	v_add_f32_e32 v40, v40, v190
	v_cndmask_b32_e32 v40, v237, v40, vcc
	v_cmp_gt_u32_e32 vcc, 16, v145
	s_waitcnt lgkmcnt(12)
	v_add_f32_e32 v41, v41, v191
	v_cndmask_b32_e32 v41, v237, v41, vcc
	v_cmp_gt_u32_e32 vcc, 16, v146
	s_waitcnt lgkmcnt(11)
	v_add_f32_e32 v42, v42, v192
	v_cndmask_b32_e32 v42, v237, v42, vcc
	v_cmp_gt_u32_e32 vcc, 16, v147
	s_waitcnt lgkmcnt(10)
	v_add_f32_e32 v43, v43, v193
	v_cndmask_b32_e32 v43, v237, v43, vcc
	v_cmp_gt_u32_e32 vcc, 16, v148
	s_waitcnt lgkmcnt(9)
	v_add_f32_e32 v44, v44, v194
	v_cndmask_b32_e32 v44, v237, v44, vcc
	v_cmp_gt_u32_e32 vcc, 16, v149
	s_waitcnt lgkmcnt(8)
	v_add_f32_e32 v45, v45, v195
	v_cndmask_b32_e32 v45, v237, v45, vcc
	v_cmp_gt_u32_e32 vcc, 16, v158
	s_waitcnt lgkmcnt(7)
	v_add_f32_e32 v46, v46, v196
	v_cndmask_b32_e32 v46, v237, v46, vcc
	v_cmp_gt_u32_e32 vcc, 16, v160
	s_waitcnt lgkmcnt(6)
	v_add_f32_e32 v47, v47, v197
	v_cndmask_b32_e32 v47, v237, v47, vcc
	v_cmp_gt_u32_e32 vcc, 16, v162
	s_waitcnt lgkmcnt(5)
	v_add_f32_e32 v48, v48, v198
	v_cndmask_b32_e32 v48, v237, v48, vcc
	v_cmp_gt_u32_e32 vcc, 16, v164
	s_waitcnt lgkmcnt(4)
	v_add_f32_e32 v49, v49, v199
	v_cndmask_b32_e32 v49, v237, v49, vcc
	v_cmp_gt_u32_e32 vcc, 16, v166
	s_waitcnt lgkmcnt(3)
	v_add_f32_e32 v50, v50, v200
	v_cndmask_b32_e32 v50, v237, v50, vcc
	v_cmp_gt_u32_e32 vcc, 16, v168
	s_waitcnt lgkmcnt(2)
	v_add_f32_e32 v51, v51, v201
	v_cndmask_b32_e32 v51, v237, v51, vcc
	v_cmp_gt_u32_e32 vcc, 16, v169
	s_waitcnt lgkmcnt(1)
	v_add_f32_e32 v52, v52, v202
	v_cndmask_b32_e32 v52, v237, v52, vcc
	v_cmp_gt_u32_e32 vcc, 16, v171
	s_waitcnt lgkmcnt(0)
	v_add_f32_e32 v53, v53, v203
	v_cndmask_b32_e32 v53, v237, v53, vcc
	s_branch .LBB0_686
.La0_p1:
	v_add_u32_e32 v235, v204, v236
	ds_read_b32 v188, v235 offset:868
	v_add_u32_e32 v235, v205, v236
	ds_read_b32 v189, v235 offset:868
	v_add_u32_e32 v235, v206, v236
	ds_read_b32 v190, v235 offset:868
	v_add_u32_e32 v235, v207, v236
	ds_read_b32 v191, v235 offset:868
	v_add_u32_e32 v235, v208, v236
	ds_read_b32 v192, v235 offset:868
	v_add_u32_e32 v235, v209, v236
	ds_read_b32 v193, v235 offset:868
	v_add_u32_e32 v235, v210, v236
	ds_read_b32 v194, v235 offset:868
	v_add_u32_e32 v235, v211, v236
	ds_read_b32 v195, v235 offset:868
	v_add_u32_e32 v235, v212, v236
	ds_read_b32 v196, v235 offset:868
	v_add_u32_e32 v235, v213, v236
	ds_read_b32 v197, v235 offset:868
	v_add_u32_e32 v235, v214, v236
	ds_read_b32 v198, v235 offset:868
	v_add_u32_e32 v235, v136, v236
	ds_read_b32 v199, v235 offset:868
	v_add_u32_e32 v235, v137, v236
	ds_read_b32 v200, v235 offset:868
	v_add_u32_e32 v235, v138, v236
	ds_read_b32 v201, v235 offset:868
	v_add_u32_e32 v235, v139, v236
	ds_read_b32 v202, v235 offset:868
	v_add_u32_e32 v235, v140, v236
	ds_read_b32 v203, v235 offset:868
	v_add_u32_e32 v234, 32, v142
	v_cmp_gt_u32_e32 vcc, 16, v234
	s_waitcnt lgkmcnt(15)
	v_add_f32_e32 v38, v38, v188
	v_cndmask_b32_e32 v38, v237, v38, vcc
	v_add_u32_e32 v234, 32, v143
	v_cmp_gt_u32_e32 vcc, 16, v234
	s_waitcnt lgkmcnt(14)
	v_add_f32_e32 v39, v39, v189
	v_cndmask_b32_e32 v39, v237, v39, vcc
	v_add_u32_e32 v234, 32, v144
	v_cmp_gt_u32_e32 vcc, 16, v234
	s_waitcnt lgkmcnt(13)
	v_add_f32_e32 v40, v40, v190
	v_cndmask_b32_e32 v40, v237, v40, vcc
	v_add_u32_e32 v234, 32, v145
	v_cmp_gt_u32_e32 vcc, 16, v234
	s_waitcnt lgkmcnt(12)
	v_add_f32_e32 v41, v41, v191
	v_cndmask_b32_e32 v41, v237, v41, vcc
	v_add_u32_e32 v234, 32, v146
	v_cmp_gt_u32_e32 vcc, 16, v234
	s_waitcnt lgkmcnt(11)
	v_add_f32_e32 v42, v42, v192
	v_cndmask_b32_e32 v42, v237, v42, vcc
	v_add_u32_e32 v234, 32, v147
	v_cmp_gt_u32_e32 vcc, 16, v234
	s_waitcnt lgkmcnt(10)
	v_add_f32_e32 v43, v43, v193
	v_cndmask_b32_e32 v43, v237, v43, vcc
	v_add_u32_e32 v234, 32, v148
	v_cmp_gt_u32_e32 vcc, 16, v234
	s_waitcnt lgkmcnt(9)
	v_add_f32_e32 v44, v44, v194
	v_cndmask_b32_e32 v44, v237, v44, vcc
	v_add_u32_e32 v234, 32, v149
	v_cmp_gt_u32_e32 vcc, 16, v234
	s_waitcnt lgkmcnt(8)
	v_add_f32_e32 v45, v45, v195
	v_cndmask_b32_e32 v45, v237, v45, vcc
	v_add_u32_e32 v234, 32, v158
	v_cmp_gt_u32_e32 vcc, 16, v234
	s_waitcnt lgkmcnt(7)
	v_add_f32_e32 v46, v46, v196
	v_cndmask_b32_e32 v46, v237, v46, vcc
	v_add_u32_e32 v234, 32, v160
	v_cmp_gt_u32_e32 vcc, 16, v234
	s_waitcnt lgkmcnt(6)
	v_add_f32_e32 v47, v47, v197
	v_cndmask_b32_e32 v47, v237, v47, vcc
	v_add_u32_e32 v234, 32, v162
	v_cmp_gt_u32_e32 vcc, 16, v234
	s_waitcnt lgkmcnt(5)
	v_add_f32_e32 v48, v48, v198
	v_cndmask_b32_e32 v48, v237, v48, vcc
	v_add_u32_e32 v234, 32, v164
	v_cmp_gt_u32_e32 vcc, 16, v234
	s_waitcnt lgkmcnt(4)
	v_add_f32_e32 v49, v49, v199
	v_cndmask_b32_e32 v49, v237, v49, vcc
	v_add_u32_e32 v234, 32, v166
	v_cmp_gt_u32_e32 vcc, 16, v234
	s_waitcnt lgkmcnt(3)
	v_add_f32_e32 v50, v50, v200
	v_cndmask_b32_e32 v50, v237, v50, vcc
	v_add_u32_e32 v234, 32, v168
	v_cmp_gt_u32_e32 vcc, 16, v234
	s_waitcnt lgkmcnt(2)
	v_add_f32_e32 v51, v51, v201
	v_cndmask_b32_e32 v51, v237, v51, vcc
	v_add_u32_e32 v234, 32, v169
	v_cmp_gt_u32_e32 vcc, 16, v234
	s_waitcnt lgkmcnt(1)
	v_add_f32_e32 v52, v52, v202
	v_cndmask_b32_e32 v52, v237, v52, vcc
	v_add_u32_e32 v234, 32, v171
	v_cmp_gt_u32_e32 vcc, 16, v234
	s_waitcnt lgkmcnt(0)
	v_add_f32_e32 v53, v53, v203
	v_cndmask_b32_e32 v53, v237, v53, vcc
	s_branch .LBB0_686
